# phase-0 precompose items (w_in pool cols @ w_pool, f32) moved from the VALU+LDS FMA loop to f32 matrix cores (v_mfma_f32_16x16x4_f32) fed by direct global loads
# speedup vs baseline: 1.0115x; 1.0070x over previous
.LBB0_39:
	v_xad_u32 v2, s33, -1, v69
	v_mov_b32_e32 v3, s33
	v_cndmask_b32_e64 v2, v3, v2, s[0:1]
	v_mad_u64_u32 v[2:3], s[12:13], v2, s34, v[66:67]
	s_movk_i32 s12, 0x3ff
	s_nop 0
	v_cmp_lt_i32_e32 vcc, s12, v2
	s_and_saveexec_b64 s[12:13], vcc
	s_xor_b64 s[12:13], exec, s[12:13]
	s_cbranch_execz .LBB0_51
	v_cmp_lt_u32_e32 vcc, s35, v2
	s_and_saveexec_b64 s[20:21], vcc
	s_xor_b64 s[20:21], exec, s[20:21]
	s_cbranch_execz .LBB0_48
	v_cmp_lt_u32_e32 vcc, s36, v2
	s_and_saveexec_b64 s[30:31], vcc
	s_xor_b64 s[30:31], exec, s[30:31]
	s_cbranch_execz .LBB0_45
	v_readfirstlane_b32 s66, v2
	v_readfirstlane_b32 s98, v88
	v_readfirstlane_b32 s99, v89
	s_nop 3
	s_sub_i32 s66, s66, 0x1300
	s_lshr_b32 s67, s66, 9
	s_and_b32 s66, s66, 0x1ff
	s_lshr_b32 s100, s66, 6
	s_lshl_b32 s100, s100, 5
	s_and_b32 s66, s66, 63
	s_lshl_b32 s66, s66, 4
	s_sub_u32 s98, s98, 0xfc00
	s_subb_u32 s99, s99, 0
	v_mbcnt_lo_u32_b32 v250, -1, 0
	v_mbcnt_hi_u32_b32 v250, -1, v250
	v_and_b32_e32 v252, 15, v250
	v_lshrrev_b32_e32 v253, 4, v250
	v_add_u32_e32 v254, s66, v252
	v_mul_u32_u24_e32 v254, 0x3000, v254
	v_lshl_add_u32 v254, v253, 6, v254
	s_lshl_b32 s101, s67, 10
	s_add_i32 s101, s101, 0x2000
	v_add_u32_e32 v254, s101, v254
	v_lshlrev_b32_e32 v255, 14, v253
	v_lshl_add_u32 v255, v252, 2, v255
	s_lshl_b32 s101, s67, 18
	v_add_u32_e32 v255, s101, v255
	s_lshl_b32 s101, s100, 2
	v_add_u32_e32 v255, s101, v255
	global_load_dwordx4 v[2:5], v254, s[58:59]
	global_load_dwordx4 v[6:9], v254, s[58:59] offset:16
	global_load_dwordx4 v[10:13], v254, s[58:59] offset:32
	global_load_dwordx4 v[14:17], v254, s[58:59] offset:48
	global_load_dwordx4 v[18:21], v254, s[58:59] offset:256
	global_load_dwordx4 v[22:25], v254, s[58:59] offset:272
	global_load_dwordx4 v[26:29], v254, s[58:59] offset:288
	global_load_dwordx4 v[30:33], v254, s[58:59] offset:304
	global_load_dwordx4 v[34:37], v254, s[58:59] offset:512
	global_load_dwordx4 v[38:41], v254, s[58:59] offset:528
	global_load_dwordx4 v[42:45], v254, s[58:59] offset:544
	global_load_dwordx4 v[46:49], v254, s[58:59] offset:560
	global_load_dwordx4 v[50:53], v254, s[58:59] offset:768
	global_load_dwordx4 v[54:57], v254, s[58:59] offset:784
	global_load_dwordx4 v[58:61], v254, s[58:59] offset:800
	global_load_dwordx4 v[62:65], v254, s[58:59] offset:816
	v_mov_b32_e32 v120, v255
	v_add_u32_e32 v121, 0x1000, v255
	v_add_u32_e32 v122, 0x2000, v255
	v_add_u32_e32 v123, 0x3000, v255
	global_load_dword v176, v120, s[98:99]
	global_load_dword v177, v120, s[98:99] offset:1024
	global_load_dword v178, v120, s[98:99] offset:2048
	global_load_dword v179, v120, s[98:99] offset:3072
	global_load_dword v180, v121, s[98:99]
	global_load_dword v181, v121, s[98:99] offset:1024
	global_load_dword v182, v121, s[98:99] offset:2048
	global_load_dword v183, v121, s[98:99] offset:3072
	global_load_dword v184, v122, s[98:99]
	global_load_dword v185, v122, s[98:99] offset:1024
	global_load_dword v186, v122, s[98:99] offset:2048
	global_load_dword v187, v122, s[98:99] offset:3072
	global_load_dword v188, v123, s[98:99]
	global_load_dword v189, v123, s[98:99] offset:1024
	global_load_dword v190, v123, s[98:99] offset:2048
	global_load_dword v191, v123, s[98:99] offset:3072
	global_load_dword v192, v120, s[98:99] offset:64
	global_load_dword v193, v120, s[98:99] offset:1088
	global_load_dword v194, v120, s[98:99] offset:2112
	global_load_dword v195, v120, s[98:99] offset:3136
	global_load_dword v196, v121, s[98:99] offset:64
	global_load_dword v197, v121, s[98:99] offset:1088
	global_load_dword v198, v121, s[98:99] offset:2112
	global_load_dword v199, v121, s[98:99] offset:3136
	global_load_dword v200, v122, s[98:99] offset:64
	global_load_dword v201, v122, s[98:99] offset:1088
	global_load_dword v202, v122, s[98:99] offset:2112
	global_load_dword v203, v122, s[98:99] offset:3136
	global_load_dword v204, v123, s[98:99] offset:64
	global_load_dword v205, v123, s[98:99] offset:1088
	global_load_dword v206, v123, s[98:99] offset:2112
	global_load_dword v207, v123, s[98:99] offset:3136
	v_mov_b32_e32 v242, 0
	v_mov_b32_e32 v246, 0
	v_mov_b32_e32 v243, 0
	v_mov_b32_e32 v247, 0
	v_mov_b32_e32 v244, 0
	v_mov_b32_e32 v248, 0
	v_mov_b32_e32 v245, 0
	v_mov_b32_e32 v249, 0
	s_waitcnt vmcnt(0)
	v_add_u32_e32 v120, 0x10000, v255
	v_add_u32_e32 v121, 0x11000, v255
	v_add_u32_e32 v122, 0x12000, v255
	v_add_u32_e32 v123, 0x13000, v255
	global_load_dword v208, v120, s[98:99]
	global_load_dword v209, v120, s[98:99] offset:1024
	global_load_dword v210, v120, s[98:99] offset:2048
	global_load_dword v211, v120, s[98:99] offset:3072
	global_load_dword v212, v121, s[98:99]
	global_load_dword v213, v121, s[98:99] offset:1024
	global_load_dword v214, v121, s[98:99] offset:2048
	global_load_dword v215, v121, s[98:99] offset:3072
	global_load_dword v216, v122, s[98:99]
	global_load_dword v217, v122, s[98:99] offset:1024
	global_load_dword v219, v122, s[98:99] offset:2048
	global_load_dword v220, v122, s[98:99] offset:3072
	global_load_dword v221, v123, s[98:99]
	global_load_dword v222, v123, s[98:99] offset:1024
	global_load_dword v223, v123, s[98:99] offset:2048
	global_load_dword v224, v123, s[98:99] offset:3072
	global_load_dword v225, v120, s[98:99] offset:64
	global_load_dword v226, v120, s[98:99] offset:1088
	global_load_dword v227, v120, s[98:99] offset:2112
	global_load_dword v228, v120, s[98:99] offset:3136
	global_load_dword v229, v121, s[98:99] offset:64
	global_load_dword v230, v121, s[98:99] offset:1088
	global_load_dword v231, v121, s[98:99] offset:2112
	global_load_dword v232, v121, s[98:99] offset:3136
	global_load_dword v233, v122, s[98:99] offset:64
	global_load_dword v234, v122, s[98:99] offset:1088
	global_load_dword v235, v122, s[98:99] offset:2112
	global_load_dword v236, v122, s[98:99] offset:3136
	global_load_dword v237, v123, s[98:99] offset:64
	global_load_dword v238, v123, s[98:99] offset:1088
	global_load_dword v239, v123, s[98:99] offset:2112
	global_load_dword v240, v123, s[98:99] offset:3136
	v_mfma_f32_16x16x4_f32 v[242:245], v2, v176, v[242:245]
	v_mfma_f32_16x16x4_f32 v[246:249], v2, v192, v[246:249]
	v_mfma_f32_16x16x4_f32 v[242:245], v3, v177, v[242:245]
	v_mfma_f32_16x16x4_f32 v[246:249], v3, v193, v[246:249]
	v_mfma_f32_16x16x4_f32 v[242:245], v4, v178, v[242:245]
	v_mfma_f32_16x16x4_f32 v[246:249], v4, v194, v[246:249]
	v_mfma_f32_16x16x4_f32 v[242:245], v5, v179, v[242:245]
	v_mfma_f32_16x16x4_f32 v[246:249], v5, v195, v[246:249]
	v_mfma_f32_16x16x4_f32 v[242:245], v6, v180, v[242:245]
	v_mfma_f32_16x16x4_f32 v[246:249], v6, v196, v[246:249]
	v_mfma_f32_16x16x4_f32 v[242:245], v7, v181, v[242:245]
	v_mfma_f32_16x16x4_f32 v[246:249], v7, v197, v[246:249]
	v_mfma_f32_16x16x4_f32 v[242:245], v8, v182, v[242:245]
	v_mfma_f32_16x16x4_f32 v[246:249], v8, v198, v[246:249]
	v_mfma_f32_16x16x4_f32 v[242:245], v9, v183, v[242:245]
	v_mfma_f32_16x16x4_f32 v[246:249], v9, v199, v[246:249]
	v_mfma_f32_16x16x4_f32 v[242:245], v10, v184, v[242:245]
	v_mfma_f32_16x16x4_f32 v[246:249], v10, v200, v[246:249]
	v_mfma_f32_16x16x4_f32 v[242:245], v11, v185, v[242:245]
	v_mfma_f32_16x16x4_f32 v[246:249], v11, v201, v[246:249]
	v_mfma_f32_16x16x4_f32 v[242:245], v12, v186, v[242:245]
	v_mfma_f32_16x16x4_f32 v[246:249], v12, v202, v[246:249]
	v_mfma_f32_16x16x4_f32 v[242:245], v13, v187, v[242:245]
	v_mfma_f32_16x16x4_f32 v[246:249], v13, v203, v[246:249]
	v_mfma_f32_16x16x4_f32 v[242:245], v14, v188, v[242:245]
	v_mfma_f32_16x16x4_f32 v[246:249], v14, v204, v[246:249]
	v_mfma_f32_16x16x4_f32 v[242:245], v15, v189, v[242:245]
	v_mfma_f32_16x16x4_f32 v[246:249], v15, v205, v[246:249]
	v_mfma_f32_16x16x4_f32 v[242:245], v16, v190, v[242:245]
	v_mfma_f32_16x16x4_f32 v[246:249], v16, v206, v[246:249]
	v_mfma_f32_16x16x4_f32 v[242:245], v17, v191, v[242:245]
	v_mfma_f32_16x16x4_f32 v[246:249], v17, v207, v[246:249]
	s_waitcnt vmcnt(0)
	v_add_u32_e32 v120, 0x20000, v255
	v_add_u32_e32 v121, 0x21000, v255
	v_add_u32_e32 v122, 0x22000, v255
	v_add_u32_e32 v123, 0x23000, v255
	global_load_dword v176, v120, s[98:99]
	global_load_dword v177, v120, s[98:99] offset:1024
	global_load_dword v178, v120, s[98:99] offset:2048
	global_load_dword v179, v120, s[98:99] offset:3072
	global_load_dword v180, v121, s[98:99]
	global_load_dword v181, v121, s[98:99] offset:1024
	global_load_dword v182, v121, s[98:99] offset:2048
	global_load_dword v183, v121, s[98:99] offset:3072
	global_load_dword v184, v122, s[98:99]
	global_load_dword v185, v122, s[98:99] offset:1024
	global_load_dword v186, v122, s[98:99] offset:2048
	global_load_dword v187, v122, s[98:99] offset:3072
	global_load_dword v188, v123, s[98:99]
	global_load_dword v189, v123, s[98:99] offset:1024
	global_load_dword v190, v123, s[98:99] offset:2048
	global_load_dword v191, v123, s[98:99] offset:3072
	global_load_dword v192, v120, s[98:99] offset:64
	global_load_dword v193, v120, s[98:99] offset:1088
	global_load_dword v194, v120, s[98:99] offset:2112
	global_load_dword v195, v120, s[98:99] offset:3136
	global_load_dword v196, v121, s[98:99] offset:64
	global_load_dword v197, v121, s[98:99] offset:1088
	global_load_dword v198, v121, s[98:99] offset:2112
	global_load_dword v199, v121, s[98:99] offset:3136
	global_load_dword v200, v122, s[98:99] offset:64
	global_load_dword v201, v122, s[98:99] offset:1088
	global_load_dword v202, v122, s[98:99] offset:2112
	global_load_dword v203, v122, s[98:99] offset:3136
	global_load_dword v204, v123, s[98:99] offset:64
	global_load_dword v205, v123, s[98:99] offset:1088
	global_load_dword v206, v123, s[98:99] offset:2112
	global_load_dword v207, v123, s[98:99] offset:3136
	v_mfma_f32_16x16x4_f32 v[242:245], v18, v208, v[242:245]
	v_mfma_f32_16x16x4_f32 v[246:249], v18, v225, v[246:249]
	v_mfma_f32_16x16x4_f32 v[242:245], v19, v209, v[242:245]
	v_mfma_f32_16x16x4_f32 v[246:249], v19, v226, v[246:249]
	v_mfma_f32_16x16x4_f32 v[242:245], v20, v210, v[242:245]
	v_mfma_f32_16x16x4_f32 v[246:249], v20, v227, v[246:249]
	v_mfma_f32_16x16x4_f32 v[242:245], v21, v211, v[242:245]
	v_mfma_f32_16x16x4_f32 v[246:249], v21, v228, v[246:249]
	v_mfma_f32_16x16x4_f32 v[242:245], v22, v212, v[242:245]
	v_mfma_f32_16x16x4_f32 v[246:249], v22, v229, v[246:249]
	v_mfma_f32_16x16x4_f32 v[242:245], v23, v213, v[242:245]
	v_mfma_f32_16x16x4_f32 v[246:249], v23, v230, v[246:249]
	v_mfma_f32_16x16x4_f32 v[242:245], v24, v214, v[242:245]
	v_mfma_f32_16x16x4_f32 v[246:249], v24, v231, v[246:249]
	v_mfma_f32_16x16x4_f32 v[242:245], v25, v215, v[242:245]
	v_mfma_f32_16x16x4_f32 v[246:249], v25, v232, v[246:249]
	v_mfma_f32_16x16x4_f32 v[242:245], v26, v216, v[242:245]
	v_mfma_f32_16x16x4_f32 v[246:249], v26, v233, v[246:249]
	v_mfma_f32_16x16x4_f32 v[242:245], v27, v217, v[242:245]
	v_mfma_f32_16x16x4_f32 v[246:249], v27, v234, v[246:249]
	v_mfma_f32_16x16x4_f32 v[242:245], v28, v219, v[242:245]
	v_mfma_f32_16x16x4_f32 v[246:249], v28, v235, v[246:249]
	v_mfma_f32_16x16x4_f32 v[242:245], v29, v220, v[242:245]
	v_mfma_f32_16x16x4_f32 v[246:249], v29, v236, v[246:249]
	v_mfma_f32_16x16x4_f32 v[242:245], v30, v221, v[242:245]
	v_mfma_f32_16x16x4_f32 v[246:249], v30, v237, v[246:249]
	v_mfma_f32_16x16x4_f32 v[242:245], v31, v222, v[242:245]
	v_mfma_f32_16x16x4_f32 v[246:249], v31, v238, v[246:249]
	v_mfma_f32_16x16x4_f32 v[242:245], v32, v223, v[242:245]
	v_mfma_f32_16x16x4_f32 v[246:249], v32, v239, v[246:249]
	v_mfma_f32_16x16x4_f32 v[242:245], v33, v224, v[242:245]
	v_mfma_f32_16x16x4_f32 v[246:249], v33, v240, v[246:249]
	s_waitcnt vmcnt(0)
	v_add_u32_e32 v120, 0x30000, v255
	v_add_u32_e32 v121, 0x31000, v255
	v_add_u32_e32 v122, 0x32000, v255
	v_add_u32_e32 v123, 0x33000, v255
	global_load_dword v208, v120, s[98:99]
	global_load_dword v209, v120, s[98:99] offset:1024
	global_load_dword v210, v120, s[98:99] offset:2048
	global_load_dword v211, v120, s[98:99] offset:3072
	global_load_dword v212, v121, s[98:99]
	global_load_dword v213, v121, s[98:99] offset:1024
	global_load_dword v214, v121, s[98:99] offset:2048
	global_load_dword v215, v121, s[98:99] offset:3072
	global_load_dword v216, v122, s[98:99]
	global_load_dword v217, v122, s[98:99] offset:1024
	global_load_dword v219, v122, s[98:99] offset:2048
	global_load_dword v220, v122, s[98:99] offset:3072
	global_load_dword v221, v123, s[98:99]
	global_load_dword v222, v123, s[98:99] offset:1024
	global_load_dword v223, v123, s[98:99] offset:2048
	global_load_dword v224, v123, s[98:99] offset:3072
	global_load_dword v225, v120, s[98:99] offset:64
	global_load_dword v226, v120, s[98:99] offset:1088
	global_load_dword v227, v120, s[98:99] offset:2112
	global_load_dword v228, v120, s[98:99] offset:3136
	global_load_dword v229, v121, s[98:99] offset:64
	global_load_dword v230, v121, s[98:99] offset:1088
	global_load_dword v231, v121, s[98:99] offset:2112
	global_load_dword v232, v121, s[98:99] offset:3136
	global_load_dword v233, v122, s[98:99] offset:64
	global_load_dword v234, v122, s[98:99] offset:1088
	global_load_dword v235, v122, s[98:99] offset:2112
	global_load_dword v236, v122, s[98:99] offset:3136
	global_load_dword v237, v123, s[98:99] offset:64
	global_load_dword v238, v123, s[98:99] offset:1088
	global_load_dword v239, v123, s[98:99] offset:2112
	global_load_dword v240, v123, s[98:99] offset:3136
	v_mfma_f32_16x16x4_f32 v[242:245], v34, v176, v[242:245]
	v_mfma_f32_16x16x4_f32 v[246:249], v34, v192, v[246:249]
	v_mfma_f32_16x16x4_f32 v[242:245], v35, v177, v[242:245]
	v_mfma_f32_16x16x4_f32 v[246:249], v35, v193, v[246:249]
	v_mfma_f32_16x16x4_f32 v[242:245], v36, v178, v[242:245]
	v_mfma_f32_16x16x4_f32 v[246:249], v36, v194, v[246:249]
	v_mfma_f32_16x16x4_f32 v[242:245], v37, v179, v[242:245]
	v_mfma_f32_16x16x4_f32 v[246:249], v37, v195, v[246:249]
	v_mfma_f32_16x16x4_f32 v[242:245], v38, v180, v[242:245]
	v_mfma_f32_16x16x4_f32 v[246:249], v38, v196, v[246:249]
	v_mfma_f32_16x16x4_f32 v[242:245], v39, v181, v[242:245]
	v_mfma_f32_16x16x4_f32 v[246:249], v39, v197, v[246:249]
	v_mfma_f32_16x16x4_f32 v[242:245], v40, v182, v[242:245]
	v_mfma_f32_16x16x4_f32 v[246:249], v40, v198, v[246:249]
	v_mfma_f32_16x16x4_f32 v[242:245], v41, v183, v[242:245]
	v_mfma_f32_16x16x4_f32 v[246:249], v41, v199, v[246:249]
	v_mfma_f32_16x16x4_f32 v[242:245], v42, v184, v[242:245]
	v_mfma_f32_16x16x4_f32 v[246:249], v42, v200, v[246:249]
	v_mfma_f32_16x16x4_f32 v[242:245], v43, v185, v[242:245]
	v_mfma_f32_16x16x4_f32 v[246:249], v43, v201, v[246:249]
	v_mfma_f32_16x16x4_f32 v[242:245], v44, v186, v[242:245]
	v_mfma_f32_16x16x4_f32 v[246:249], v44, v202, v[246:249]
	v_mfma_f32_16x16x4_f32 v[242:245], v45, v187, v[242:245]
	v_mfma_f32_16x16x4_f32 v[246:249], v45, v203, v[246:249]
	v_mfma_f32_16x16x4_f32 v[242:245], v46, v188, v[242:245]
	v_mfma_f32_16x16x4_f32 v[246:249], v46, v204, v[246:249]
	v_mfma_f32_16x16x4_f32 v[242:245], v47, v189, v[242:245]
	v_mfma_f32_16x16x4_f32 v[246:249], v47, v205, v[246:249]
	v_mfma_f32_16x16x4_f32 v[242:245], v48, v190, v[242:245]
	v_mfma_f32_16x16x4_f32 v[246:249], v48, v206, v[246:249]
	v_mfma_f32_16x16x4_f32 v[242:245], v49, v191, v[242:245]
	v_mfma_f32_16x16x4_f32 v[246:249], v49, v207, v[246:249]
	s_waitcnt vmcnt(0)
	v_mfma_f32_16x16x4_f32 v[242:245], v50, v208, v[242:245]
	v_mfma_f32_16x16x4_f32 v[246:249], v50, v225, v[246:249]
	v_mfma_f32_16x16x4_f32 v[242:245], v51, v209, v[242:245]
	v_mfma_f32_16x16x4_f32 v[246:249], v51, v226, v[246:249]
	v_mfma_f32_16x16x4_f32 v[242:245], v52, v210, v[242:245]
	v_mfma_f32_16x16x4_f32 v[246:249], v52, v227, v[246:249]
	v_mfma_f32_16x16x4_f32 v[242:245], v53, v211, v[242:245]
	v_mfma_f32_16x16x4_f32 v[246:249], v53, v228, v[246:249]
	v_mfma_f32_16x16x4_f32 v[242:245], v54, v212, v[242:245]
	v_mfma_f32_16x16x4_f32 v[246:249], v54, v229, v[246:249]
	v_mfma_f32_16x16x4_f32 v[242:245], v55, v213, v[242:245]
	v_mfma_f32_16x16x4_f32 v[246:249], v55, v230, v[246:249]
	v_mfma_f32_16x16x4_f32 v[242:245], v56, v214, v[242:245]
	v_mfma_f32_16x16x4_f32 v[246:249], v56, v231, v[246:249]
	v_mfma_f32_16x16x4_f32 v[242:245], v57, v215, v[242:245]
	v_mfma_f32_16x16x4_f32 v[246:249], v57, v232, v[246:249]
	v_mfma_f32_16x16x4_f32 v[242:245], v58, v216, v[242:245]
	v_mfma_f32_16x16x4_f32 v[246:249], v58, v233, v[246:249]
	v_mfma_f32_16x16x4_f32 v[242:245], v59, v217, v[242:245]
	v_mfma_f32_16x16x4_f32 v[246:249], v59, v234, v[246:249]
	v_mfma_f32_16x16x4_f32 v[242:245], v60, v219, v[242:245]
	v_mfma_f32_16x16x4_f32 v[246:249], v60, v235, v[246:249]
	v_mfma_f32_16x16x4_f32 v[242:245], v61, v220, v[242:245]
	v_mfma_f32_16x16x4_f32 v[246:249], v61, v236, v[246:249]
	v_mfma_f32_16x16x4_f32 v[242:245], v62, v221, v[242:245]
	v_mfma_f32_16x16x4_f32 v[246:249], v62, v237, v[246:249]
	v_mfma_f32_16x16x4_f32 v[242:245], v63, v222, v[242:245]
	v_mfma_f32_16x16x4_f32 v[246:249], v63, v238, v[246:249]
	v_mfma_f32_16x16x4_f32 v[242:245], v64, v223, v[242:245]
	v_mfma_f32_16x16x4_f32 v[246:249], v64, v239, v[246:249]
	v_mfma_f32_16x16x4_f32 v[242:245], v65, v224, v[242:245]
	v_mfma_f32_16x16x4_f32 v[246:249], v65, v240, v[246:249]
	s_nop 7
	s_nop 7
	s_lshl_b32 s101, s67, 8
	s_add_i32 s101, s101, s100
	s_add_i32 s101, s101, 0x800
	v_add_u32_e32 v120, s101, v252
	v_lshlrev_b32_e32 v120, 10, v120
	v_lshl_add_u32 v120, v253, 2, v120
	v_add_u32_e32 v120, s66, v120
	v_lshlrev_b32_e32 v120, 1, v120
	v_add_u32_e32 v121, 0x8000, v120
	v_cvt_pk_bf16_f32 v122, v242, v243
	v_cvt_pk_bf16_f32 v123, v244, v245
	v_cvt_pk_bf16_f32 v124, v246, v247
	v_cvt_pk_bf16_f32 v125, v248, v249
	global_store_dwordx2 v120, v[122:123], s[14:15]
	global_store_dwordx2 v121, v[124:125], s[14:15]
